# best5 + GEMM1 K-loop: 16 LDS-DMA issues per iteration use SGPR base + 32-bit VGPR offset (no per-issue 64-bit VALU address add)
# speedup vs baseline: 1.0047x; 1.0027x over previous
; #define PG8_STAGE(bufoff, gbase, voff) do { _Pragma("unroll") for (int _i = 0; _i < 2; ++_i) \
;         __builtin_amdgcn_global_load_lds((const unsigned*)((const char*)(gbase) + (voff)[_i]), (PG8_LAS unsigned*)(lds + (bufoff) + ldsw + _i * 8192), 16, 0, 0); } while (0)
; #define PG8_LDA(dst, b, h) do { _Pragma("unroll") for (int m = 0; m < 4; ++m) _Pragma("unroll") for (int k = 0; k < 2; ++k) dst[m][k] = *(const PG8_LAS bf16x8*)(lds + PG8_SA(b, h) + aoff + m * 2048 + k * 1024); } while (0)
; #define PG8_LDB(dst, b, h) do { _Pragma("unroll") for (int n = 0; n < 2; ++n) _Pragma("unroll") for (int k = 0; k < 2; ++k) dst[n][k] = *(const PG8_LAS bf16x8*)(lds + PG8_SB(b, h) + boff + n * 2048 + k * 1024); } while (0)
; #define PG8_MMA(ai, bj, At, Bt) do { __builtin_amdgcn_s_setprio(1); _Pragma("unroll") for (int m = 0; m < 4; ++m) _Pragma("unroll") for (int n = 0; n < 2; ++n) _Pragma("unroll") for (int k = 0; k < 2; ++k) \
;         acc[ai][bj][m][n] = __builtin_amdgcn_mfma_f32_16x16x32_bf16(Bt[n][k], At[m][k], acc[ai][bj][m][n], 0, 0, 0); __builtin_amdgcn_s_setprio(0); } while (0)
; #define PG8_WAIT_V(n) asm volatile("s_waitcnt vmcnt(" #n ")" ::: "memory")
; #define PG8_WAIT_L(n) asm volatile("s_waitcnt lgkmcnt(" #n ")" ::: "memory")
; #define PG8_BAR __builtin_amdgcn_s_barrier()
; #define PG8_SCHED __builtin_amdgcn_sched_barrier(0)
; template <class Epi, class Sched, bool ALIGN_EPI = false, bool SP2 = false>
; __device__ __forceinline__ void gemm_phase(PG8_LAS unsigned char* lds, const Gemm g, const Sched& S, const Epi& E) {
;     ...
;             PG8_LDB(B0, 0, 0); PG8_LDB(B1, 0, 1); PG8_SCHED; PG8_LDA(At, 0, 0); PG8_STAGE(PG8_SA(1, 1), a1 + hstep, voffA);
;             PG8_WAIT_V(8); PG8_WAIT_L(0); PG8_BAR; PG8_MMA(0, 0, At, B0); PG8_MMA(0, 1, At, B1); PG8_BAR; PG8_SCHED;
;             PG8_LDA(At, 0, 1); PG8_STAGE(PG8_SB(0, 0), b2, voffB); PG8_STAGE(PG8_SB(0, 1), b2 + hstep, voffB); PG8_STAGE(PG8_SA(0, 0), a2, voffA);
;             PG8_WAIT_V(8); PG8_WAIT_L(0); PG8_BAR; PG8_MMA(1, 0, At, B0); PG8_MMA(1, 1, At, B1); PG8_BAR; PG8_SCHED;
.LBB0_399:
	v_or_b32_e32 v142, 0x10000, v141
	v_add_u32_e32 v146, 0x10400, v141
	v_add_u32_e32 v150, 0x10800, v141
	v_add_u32_e32 v154, 0x10c00, v141
	v_or_b32_e32 v158, 0x14000, v141
	v_add_u32_e32 v162, 0x14400, v141
	v_add_u32_e32 v166, 0x14800, v141
	v_add_u32_e32 v170, 0x14c00, v141
	s_add_i32 s74, s62, 2
	ds_read_b128 v[142:145], v142
	ds_read_b128 v[146:149], v146
	ds_read_b128 v[150:153], v150
	ds_read_b128 v[154:157], v154
	ds_read_b128 v[158:161], v158
	ds_read_b128 v[162:165], v162
	ds_read_b128 v[166:169], v166
	ds_read_b128 v[170:173], v170
	s_add_u32 s75, s60, 0x80
	s_addc_u32 s63, s61, 0
	s_cmp_eq_u32 s68, s62
	s_cselect_b32 s62, s40, s75
	s_cselect_b32 s63, s41, s63
	s_cselect_b32 s77, s53, s73
	s_cselect_b32 s76, s52, s55
	s_add_i32 m0, s12, 0xc000
	ds_read_b128 v[174:177], v140
	ds_read_b128 v[178:181], v140 offset:1024
	ds_read_b128 v[182:185], v140 offset:2048
	ds_read_b128 v[186:189], v140 offset:3072
	ds_read_b128 v[190:193], v140 offset:4096
	ds_read_b128 v[202:205], v140 offset:5120
	ds_read_b128 v[206:209], v140 offset:6144
	ds_read_b128 v[230:233], v140 offset:7168
	global_load_lds_dwordx4 v136, s[60:61]
	s_add_i32 m0, s12, 0xe000
	s_nop 0
	global_load_lds_dwordx4 v138, s[60:61]
	s_waitcnt vmcnt(8)
	s_waitcnt lgkmcnt(0)
	s_barrier
	s_setprio 1
	s_waitcnt lgkmcnt(0)
	v_mfma_f32_16x16x32_bf16 v[126:129], v[142:145], v[174:177], v[126:129]
	v_mfma_f32_16x16x32_bf16 v[122:125], v[150:153], v[174:177], v[122:125]
	v_mfma_f32_16x16x32_bf16 v[118:121], v[142:145], v[182:185], v[118:121]
	v_mfma_f32_16x16x32_bf16 v[114:117], v[150:153], v[182:185], v[114:117]
	v_mfma_f32_16x16x32_bf16 v[110:113], v[142:145], v[190:193], v[110:113]
	v_mfma_f32_16x16x32_bf16 v[106:109], v[150:153], v[190:193], v[106:109]
	v_mfma_f32_16x16x32_bf16 v[102:105], v[142:145], v[206:209], v[102:105]
	v_mfma_f32_16x16x32_bf16 v[98:101], v[150:153], v[206:209], v[98:101]
	v_mfma_f32_16x16x32_bf16 v[126:129], v[146:149], v[178:181], v[126:129]
	v_mfma_f32_16x16x32_bf16 v[122:125], v[154:157], v[178:181], v[122:125]
	v_mfma_f32_16x16x32_bf16 v[118:121], v[146:149], v[186:189], v[118:121]
	v_mfma_f32_16x16x32_bf16 v[114:117], v[154:157], v[186:189], v[114:117]
	v_mfma_f32_16x16x32_bf16 v[110:113], v[146:149], v[202:205], v[110:113]
	v_mfma_f32_16x16x32_bf16 v[106:109], v[154:157], v[202:205], v[106:109]
	v_mfma_f32_16x16x32_bf16 v[102:105], v[146:149], v[230:233], v[102:105]
	v_mfma_f32_16x16x32_bf16 v[98:101], v[154:157], v[230:233], v[98:101]
	s_setprio 0
	s_setprio 1
	v_mfma_f32_16x16x32_bf16 v[68:71], v[158:161], v[174:177], v[68:71]
	v_mfma_f32_16x16x32_bf16 v[64:67], v[166:169], v[174:177], v[64:67]
	v_mfma_f32_16x16x32_bf16 v[60:63], v[158:161], v[182:185], v[60:63]
	v_mfma_f32_16x16x32_bf16 v[56:59], v[166:169], v[182:185], v[56:59]
	v_mfma_f32_16x16x32_bf16 v[52:55], v[158:161], v[190:193], v[52:55]
	v_mfma_f32_16x16x32_bf16 v[48:51], v[166:169], v[190:193], v[48:51]
	v_mfma_f32_16x16x32_bf16 v[44:47], v[158:161], v[206:209], v[44:47]
	v_mfma_f32_16x16x32_bf16 v[40:43], v[166:169], v[206:209], v[40:43]
	v_mfma_f32_16x16x32_bf16 v[68:71], v[162:165], v[178:181], v[68:71]
	v_mfma_f32_16x16x32_bf16 v[64:67], v[170:173], v[178:181], v[64:67]
	v_mfma_f32_16x16x32_bf16 v[60:63], v[162:165], v[186:189], v[60:63]
	v_mfma_f32_16x16x32_bf16 v[56:59], v[170:173], v[186:189], v[56:59]
	v_mfma_f32_16x16x32_bf16 v[52:55], v[162:165], v[202:205], v[52:55]
	v_mfma_f32_16x16x32_bf16 v[48:51], v[170:173], v[202:205], v[48:51]
	v_mfma_f32_16x16x32_bf16 v[44:47], v[162:165], v[230:233], v[44:47]
	v_mfma_f32_16x16x32_bf16 v[40:43], v[170:173], v[230:233], v[40:43]
	s_setprio 0
	s_barrier
	s_mov_b32 m0, s13
	ds_read_b128 v[174:177], v140 offset:16384
	ds_read_b128 v[178:181], v140 offset:17408
	ds_read_b128 v[182:185], v140 offset:18432
	ds_read_b128 v[186:189], v140 offset:19456
	ds_read_b128 v[190:193], v140 offset:20480
	ds_read_b128 v[202:205], v140 offset:21504
	ds_read_b128 v[206:209], v140 offset:22528
	ds_read_b128 v[230:233], v140 offset:23552
	global_load_lds_dwordx4 v96, s[76:77]
	s_mov_b32 m0, s16
	s_nop 0
	global_load_lds_dwordx4 v130, s[76:77]
	s_add_u32 s98, s76, s8
	s_addc_u32 s99, s77, s9
	s_add_u32 s76, s76, s42
	s_addc_u32 s77, s77, s43
	s_add_u32 s100, s76, s8
	s_addc_u32 s101, s77, s9
	s_mov_b32 m0, s17
	s_nop 0
	global_load_lds_dwordx4 v96, s[76:77]
	s_mov_b32 m0, s20
	s_nop 0
	global_load_lds_dwordx4 v130, s[76:77]
	s_mov_b32 m0, s12
	s_nop 0
	global_load_lds_dwordx4 v134, s[62:63]
	s_mov_b32 m0, s21
	s_nop 0
	global_load_lds_dwordx4 v132, s[62:63]
	s_waitcnt vmcnt(8)
	s_waitcnt lgkmcnt(0)
	s_barrier
; #define PG8_STAGE(bufoff, gbase, voff) do { _Pragma("unroll") for (int _i = 0; _i < 2; ++_i) \
;         __builtin_amdgcn_global_load_lds((const unsigned*)((const char*)(gbase) + (voff)[_i]), (PG8_LAS unsigned*)(lds + (bufoff) + ldsw + _i * 8192), 16, 0, 0); } while (0)
; #define PG8_LDA(dst, b, h) do { _Pragma("unroll") for (int m = 0; m < 4; ++m) _Pragma("unroll") for (int k = 0; k < 2; ++k) dst[m][k] = *(const PG8_LAS bf16x8*)(lds + PG8_SA(b, h) + aoff + m * 2048 + k * 1024); } while (0)
; #define PG8_LDB(dst, b, h) do { _Pragma("unroll") for (int n = 0; n < 2; ++n) _Pragma("unroll") for (int k = 0; k < 2; ++k) dst[n][k] = *(const PG8_LAS bf16x8*)(lds + PG8_SB(b, h) + boff + n * 2048 + k * 1024); } while (0)
; #define PG8_MMA(ai, bj, At, Bt) do { __builtin_amdgcn_s_setprio(1); _Pragma("unroll") for (int m = 0; m < 4; ++m) _Pragma("unroll") for (int n = 0; n < 2; ++n) _Pragma("unroll") for (int k = 0; k < 2; ++k) \
;         acc[ai][bj][m][n] = __builtin_amdgcn_mfma_f32_16x16x32_bf16(Bt[n][k], At[m][k], acc[ai][bj][m][n], 0, 0, 0); __builtin_amdgcn_s_setprio(0); } while (0)
; #define PG8_WAIT_V(n) asm volatile("s_waitcnt vmcnt(" #n ")" ::: "memory")
; #define PG8_WAIT_L(n) asm volatile("s_waitcnt lgkmcnt(" #n ")" ::: "memory")
; #define PG8_BAR __builtin_amdgcn_s_barrier()
; #define PG8_SCHED __builtin_amdgcn_sched_barrier(0)
; template <class Epi, class Sched, bool ALIGN_EPI = false, bool SP2 = false>
; __device__ __forceinline__ void gemm_phase(PG8_LAS unsigned char* lds, const Gemm g, const Sched& S, const Epi& E) {
;     ...
;             PG8_WAIT_V(8); PG8_WAIT_L(0); PG8_BAR; PG8_MMA(1, 0, At, B0); PG8_MMA(1, 1, At, B1); PG8_BAR; PG8_SCHED;
;             PG8_LDB(B0, 1, 0); PG8_LDB(B1, 1, 1); PG8_SCHED; PG8_LDA(At, 1, 0); PG8_STAGE(PG8_SA(0, 1), a2 + hstep, voffA);
;             PG8_WAIT_V(8); PG8_WAIT_L(0); PG8_BAR; PG8_MMA(0, 0, At, B0); PG8_MMA(0, 1, At, B1); PG8_BAR; PG8_SCHED;
	s_setprio 1
	s_waitcnt lgkmcnt(0)
	v_mfma_f32_16x16x32_bf16 v[92:95], v[142:145], v[174:177], v[92:95]
	v_mfma_f32_16x16x32_bf16 v[88:91], v[150:153], v[174:177], v[88:91]
	v_mfma_f32_16x16x32_bf16 v[84:87], v[142:145], v[182:185], v[84:87]
	v_mfma_f32_16x16x32_bf16 v[80:83], v[150:153], v[182:185], v[80:83]
	v_mfma_f32_16x16x32_bf16 v[76:79], v[142:145], v[190:193], v[76:79]
	v_mfma_f32_16x16x32_bf16 v[72:75], v[150:153], v[190:193], v[72:75]
	v_mfma_f32_16x16x32_bf16 v[12:15], v[142:145], v[206:209], v[12:15]
	v_mfma_f32_16x16x32_bf16 v[8:11], v[150:153], v[206:209], v[8:11]
	v_mfma_f32_16x16x32_bf16 v[92:95], v[146:149], v[178:181], v[92:95]
	v_mfma_f32_16x16x32_bf16 v[88:91], v[154:157], v[178:181], v[88:91]
	v_mfma_f32_16x16x32_bf16 v[84:87], v[146:149], v[186:189], v[84:87]
	v_mfma_f32_16x16x32_bf16 v[80:83], v[154:157], v[186:189], v[80:83]
	v_mfma_f32_16x16x32_bf16 v[76:79], v[146:149], v[202:205], v[76:79]
	v_mfma_f32_16x16x32_bf16 v[72:75], v[154:157], v[202:205], v[72:75]
	v_mfma_f32_16x16x32_bf16 v[12:15], v[146:149], v[230:233], v[12:15]
	v_mfma_f32_16x16x32_bf16 v[8:11], v[154:157], v[230:233], v[8:11]
	s_setprio 0
	s_setprio 1
	v_mfma_f32_16x16x32_bf16 v[36:39], v[158:161], v[174:177], v[36:39]
	v_mfma_f32_16x16x32_bf16 v[32:35], v[166:169], v[174:177], v[32:35]
	v_mfma_f32_16x16x32_bf16 v[28:31], v[158:161], v[182:185], v[28:31]
	v_mfma_f32_16x16x32_bf16 v[24:27], v[166:169], v[182:185], v[24:27]
	v_mfma_f32_16x16x32_bf16 v[20:23], v[158:161], v[190:193], v[20:23]
	v_mfma_f32_16x16x32_bf16 v[16:19], v[166:169], v[190:193], v[16:19]
	v_mfma_f32_16x16x32_bf16 v[4:7], v[158:161], v[206:209], v[4:7]
	v_mfma_f32_16x16x32_bf16 v[0:3], v[166:169], v[206:209], v[0:3]
	v_mfma_f32_16x16x32_bf16 v[36:39], v[162:165], v[178:181], v[36:39]
	v_mfma_f32_16x16x32_bf16 v[32:35], v[170:173], v[178:181], v[32:35]
	v_mfma_f32_16x16x32_bf16 v[28:31], v[162:165], v[186:189], v[28:31]
	v_mfma_f32_16x16x32_bf16 v[24:27], v[170:173], v[186:189], v[24:27]
	v_mfma_f32_16x16x32_bf16 v[20:23], v[162:165], v[202:205], v[20:23]
	v_mfma_f32_16x16x32_bf16 v[16:19], v[170:173], v[202:205], v[16:19]
	v_mfma_f32_16x16x32_bf16 v[4:7], v[162:165], v[230:233], v[4:7]
	v_mfma_f32_16x16x32_bf16 v[0:3], v[170:173], v[230:233], v[0:3]
	s_setprio 0
	s_barrier
	v_or_b32_e32 v142, 0x18000, v141
	v_add_u32_e32 v146, 0x18400, v141
	v_add_u32_e32 v150, 0x18800, v141
	v_add_u32_e32 v154, 0x18c00, v141
	v_or_b32_e32 v158, 0x1c000, v141
	v_add_u32_e32 v162, 0x1c400, v141
	v_add_u32_e32 v166, 0x1c800, v141
	v_add_u32_e32 v170, 0x1cc00, v141
	ds_read_b128 v[142:145], v142
	ds_read_b128 v[146:149], v146
	ds_read_b128 v[150:153], v150
	ds_read_b128 v[154:157], v154
	ds_read_b128 v[158:161], v158
	ds_read_b128 v[162:165], v162
	ds_read_b128 v[166:169], v166
	ds_read_b128 v[170:173], v170
	s_add_u32 s62, s62, s42
	s_addc_u32 s63, s63, s43
	s_mov_b32 m0, s22
	ds_read_b128 v[174:177], v140 offset:32768
	ds_read_b128 v[178:181], v140 offset:33792
	ds_read_b128 v[182:185], v140 offset:34816
	ds_read_b128 v[186:189], v140 offset:35840
	ds_read_b128 v[190:193], v140 offset:36864
	ds_read_b128 v[202:205], v140 offset:37888
	ds_read_b128 v[206:209], v140 offset:38912
	ds_read_b128 v[230:233], v140 offset:39936
	global_load_lds_dwordx4 v134, s[62:63]
	s_mov_b32 m0, s23
	s_nop 0
	global_load_lds_dwordx4 v132, s[62:63]
	s_waitcnt vmcnt(8)
	s_waitcnt lgkmcnt(0)
	s_barrier
	s_setprio 1
	s_waitcnt lgkmcnt(0)
	v_mfma_f32_16x16x32_bf16 v[126:129], v[142:145], v[174:177], v[126:129]
	v_mfma_f32_16x16x32_bf16 v[122:125], v[150:153], v[174:177], v[122:125]
	v_mfma_f32_16x16x32_bf16 v[118:121], v[142:145], v[182:185], v[118:121]
	v_mfma_f32_16x16x32_bf16 v[114:117], v[150:153], v[182:185], v[114:117]
	v_mfma_f32_16x16x32_bf16 v[110:113], v[142:145], v[190:193], v[110:113]
	v_mfma_f32_16x16x32_bf16 v[106:109], v[150:153], v[190:193], v[106:109]
	v_mfma_f32_16x16x32_bf16 v[102:105], v[142:145], v[206:209], v[102:105]
	v_mfma_f32_16x16x32_bf16 v[98:101], v[150:153], v[206:209], v[98:101]
	v_mfma_f32_16x16x32_bf16 v[126:129], v[146:149], v[178:181], v[126:129]
	v_mfma_f32_16x16x32_bf16 v[122:125], v[154:157], v[178:181], v[122:125]
	v_mfma_f32_16x16x32_bf16 v[118:121], v[146:149], v[186:189], v[118:121]
	v_mfma_f32_16x16x32_bf16 v[114:117], v[154:157], v[186:189], v[114:117]
	v_mfma_f32_16x16x32_bf16 v[110:113], v[146:149], v[202:205], v[110:113]
	v_mfma_f32_16x16x32_bf16 v[106:109], v[154:157], v[202:205], v[106:109]
	v_mfma_f32_16x16x32_bf16 v[102:105], v[146:149], v[230:233], v[102:105]
	v_mfma_f32_16x16x32_bf16 v[98:101], v[154:157], v[230:233], v[98:101]
	s_setprio 0
	s_setprio 1
	v_mfma_f32_16x16x32_bf16 v[68:71], v[158:161], v[174:177], v[68:71]
	v_mfma_f32_16x16x32_bf16 v[64:67], v[166:169], v[174:177], v[64:67]
	v_mfma_f32_16x16x32_bf16 v[60:63], v[158:161], v[182:185], v[60:63]
	v_mfma_f32_16x16x32_bf16 v[56:59], v[166:169], v[182:185], v[56:59]
	v_mfma_f32_16x16x32_bf16 v[52:55], v[158:161], v[190:193], v[52:55]
	v_mfma_f32_16x16x32_bf16 v[48:51], v[166:169], v[190:193], v[48:51]
	v_mfma_f32_16x16x32_bf16 v[44:47], v[158:161], v[206:209], v[44:47]
	v_mfma_f32_16x16x32_bf16 v[40:43], v[166:169], v[206:209], v[40:43]
	v_mfma_f32_16x16x32_bf16 v[68:71], v[162:165], v[178:181], v[68:71]
	v_mfma_f32_16x16x32_bf16 v[64:67], v[170:173], v[178:181], v[64:67]
	v_mfma_f32_16x16x32_bf16 v[60:63], v[162:165], v[186:189], v[60:63]
	v_mfma_f32_16x16x32_bf16 v[56:59], v[170:173], v[186:189], v[56:59]
	v_mfma_f32_16x16x32_bf16 v[52:55], v[162:165], v[202:205], v[52:55]
	v_mfma_f32_16x16x32_bf16 v[48:51], v[170:173], v[202:205], v[48:51]
	v_mfma_f32_16x16x32_bf16 v[44:47], v[162:165], v[230:233], v[44:47]
	v_mfma_f32_16x16x32_bf16 v[40:43], v[170:173], v[230:233], v[40:43]
	s_setprio 0
	s_barrier
; #define PG8_STAGE(bufoff, gbase, voff) do { _Pragma("unroll") for (int _i = 0; _i < 2; ++_i) \
;         __builtin_amdgcn_global_load_lds((const unsigned*)((const char*)(gbase) + (voff)[_i]), (PG8_LAS unsigned*)(lds + (bufoff) + ldsw + _i * 8192), 16, 0, 0); } while (0)
; #define PG8_LDA(dst, b, h) do { _Pragma("unroll") for (int m = 0; m < 4; ++m) _Pragma("unroll") for (int k = 0; k < 2; ++k) dst[m][k] = *(const PG8_LAS bf16x8*)(lds + PG8_SA(b, h) + aoff + m * 2048 + k * 1024); } while (0)
; #define PG8_MMA(ai, bj, At, Bt) do { __builtin_amdgcn_s_setprio(1); _Pragma("unroll") for (int m = 0; m < 4; ++m) _Pragma("unroll") for (int n = 0; n < 2; ++n) _Pragma("unroll") for (int k = 0; k < 2; ++k) \
;         acc[ai][bj][m][n] = __builtin_amdgcn_mfma_f32_16x16x32_bf16(Bt[n][k], At[m][k], acc[ai][bj][m][n], 0, 0, 0); __builtin_amdgcn_s_setprio(0); } while (0)
; #define PG8_WAIT_V(n) asm volatile("s_waitcnt vmcnt(" #n ")" ::: "memory")
; #define PG8_WAIT_L(n) asm volatile("s_waitcnt lgkmcnt(" #n ")" ::: "memory")
; #define PG8_BAR __builtin_amdgcn_s_barrier()
; #define PG8_SCHED __builtin_amdgcn_sched_barrier(0)
; template <class Epi, class Sched, bool ALIGN_EPI = false, bool SP2 = false>
; __device__ __forceinline__ void gemm_phase(PG8_LAS unsigned char* lds, const Gemm g, const Sched& S, const Epi& E) {
;     ...
;         for (int t = 0; t < nt; t += 2) {
;     ...
;             PG8_LDA(At, 1, 1); PG8_STAGE(PG8_SB(1, 0), b3, voffB); PG8_STAGE(PG8_SB(1, 1), b3 + hstep, voffB); PG8_STAGE(PG8_SA(1, 0), a3, voffA);
;             PG8_WAIT_V(8); PG8_WAIT_L(0); PG8_BAR; PG8_MMA(1, 0, At, B0); PG8_MMA(1, 1, At, B1); PG8_BAR; PG8_SCHED;
	s_mov_b32 m0, s31
	ds_read_b128 v[174:177], v140 offset:49152
	ds_read_b128 v[178:181], v140 offset:50176
	ds_read_b128 v[182:185], v140 offset:51200
	ds_read_b128 v[186:189], v140 offset:52224
	ds_read_b128 v[190:193], v140 offset:53248
	ds_read_b128 v[202:205], v140 offset:54272
	ds_read_b128 v[206:209], v140 offset:55296
	ds_read_b128 v[230:233], v140 offset:56320
	global_load_lds_dwordx4 v96, s[98:99]
	s_mov_b32 m0, s34
	s_nop 0
	global_load_lds_dwordx4 v130, s[98:99]
	s_mov_b32 m0, s65
	s_nop 0
	global_load_lds_dwordx4 v96, s[100:101]
	s_mov_b32 m0, s66
	s_nop 0
	global_load_lds_dwordx4 v130, s[100:101]
	s_sub_u32 s98, s62, s42
	s_subb_u32 s99, s63, s43
	s_add_u32 s98, s98, s8
	s_addc_u32 s99, s99, s9
	s_mov_b32 m0, s36
	s_nop 0
	global_load_lds_dwordx4 v134, s[98:99]
	s_mov_b32 m0, s64
	s_nop 0
	global_load_lds_dwordx4 v132, s[98:99]
	s_waitcnt vmcnt(8)
	s_waitcnt lgkmcnt(0)
	s_barrier
	s_setprio 1
	s_waitcnt lgkmcnt(0)
	v_mfma_f32_16x16x32_bf16 v[92:95], v[142:145], v[174:177], v[92:95]
	v_mfma_f32_16x16x32_bf16 v[88:91], v[150:153], v[174:177], v[88:91]
	v_mfma_f32_16x16x32_bf16 v[84:87], v[142:145], v[182:185], v[84:87]
	v_mfma_f32_16x16x32_bf16 v[80:83], v[150:153], v[182:185], v[80:83]
	v_mfma_f32_16x16x32_bf16 v[76:79], v[142:145], v[190:193], v[76:79]
	v_mfma_f32_16x16x32_bf16 v[72:75], v[150:153], v[190:193], v[72:75]
	v_mfma_f32_16x16x32_bf16 v[12:15], v[142:145], v[206:209], v[12:15]
	v_mfma_f32_16x16x32_bf16 v[8:11], v[150:153], v[206:209], v[8:11]
	v_mfma_f32_16x16x32_bf16 v[92:95], v[146:149], v[178:181], v[92:95]
	v_mfma_f32_16x16x32_bf16 v[88:91], v[154:157], v[178:181], v[88:91]
	v_mfma_f32_16x16x32_bf16 v[84:87], v[146:149], v[186:189], v[84:87]
	v_mfma_f32_16x16x32_bf16 v[80:83], v[154:157], v[186:189], v[80:83]
	v_mfma_f32_16x16x32_bf16 v[76:79], v[146:149], v[202:205], v[76:79]
	v_mfma_f32_16x16x32_bf16 v[72:75], v[154:157], v[202:205], v[72:75]
	v_mfma_f32_16x16x32_bf16 v[12:15], v[146:149], v[230:233], v[12:15]
	v_mfma_f32_16x16x32_bf16 v[8:11], v[154:157], v[230:233], v[8:11]
	s_setprio 0
	s_setprio 1
	v_mfma_f32_16x16x32_bf16 v[36:39], v[158:161], v[174:177], v[36:39]
	v_mfma_f32_16x16x32_bf16 v[32:35], v[166:169], v[174:177], v[32:35]
	v_mfma_f32_16x16x32_bf16 v[28:31], v[158:161], v[182:185], v[28:31]
	v_mfma_f32_16x16x32_bf16 v[24:27], v[166:169], v[182:185], v[24:27]
	v_mfma_f32_16x16x32_bf16 v[20:23], v[158:161], v[190:193], v[20:23]
	v_mfma_f32_16x16x32_bf16 v[16:19], v[166:169], v[190:193], v[16:19]
	v_mfma_f32_16x16x32_bf16 v[4:7], v[158:161], v[206:209], v[4:7]
	v_mfma_f32_16x16x32_bf16 v[0:3], v[166:169], v[206:209], v[0:3]
	v_mfma_f32_16x16x32_bf16 v[36:39], v[162:165], v[178:181], v[36:39]
	v_mfma_f32_16x16x32_bf16 v[32:35], v[170:173], v[178:181], v[32:35]
	v_mfma_f32_16x16x32_bf16 v[28:31], v[162:165], v[186:189], v[28:31]
	v_mfma_f32_16x16x32_bf16 v[24:27], v[170:173], v[186:189], v[24:27]
	v_mfma_f32_16x16x32_bf16 v[20:23], v[162:165], v[202:205], v[20:23]
	v_mfma_f32_16x16x32_bf16 v[16:19], v[170:173], v[202:205], v[16:19]
	v_mfma_f32_16x16x32_bf16 v[4:7], v[162:165], v[230:233], v[4:7]
	v_mfma_f32_16x16x32_bf16 v[0:3], v[170:173], v[230:233], v[0:3]
	s_setprio 0
	s_barrier
	s_add_u32 s60, s60, 0x100
	s_addc_u32 s61, s61, 0
	s_add_u32 s55, s55, 0x100
	s_addc_u32 s73, s73, 0
	s_cmp_ge_i32 s74, s67
	s_mov_b32 s62, s74
	s_cbranch_scc0 .LBB0_399
	s_and_b64 vcc, exec, s[50:51]
	s_cbranch_vccz .LBB0_410
